# speedup vs baseline: 1.0299x; 1.0067x over previous
; __global__ void __launch_bounds__(NTHREADS, 2) fwd_megakernel(Params p_arg) {
;     ...
;       const float* gt = modl + (size_t)(brow >> 12) * 6144 + 2048;
; #pragma unroll
;       for (int n = 0; n < 4; ++n) {
;         const float4 g4 = *(const float4*)(gt + cofs + n * 16);
; #pragma unroll
;         for (int m = 0; m < 8; ++m) {
;           const size_t row = (size_t)brow + wr * 128 + m * 16 + fr;
;           float4 xo = *(const float4*)(xin + row * 1024 + cofs + n * 16);
;           xo.x += g4.x * acc[m][n][0]; xo.y += g4.y * acc[m][n][1]; xo.z += g4.z * acc[m][n][2]; xo.w += g4.w * acc[m][n][3];
;           *(float4*)(pk->out + row * 1024 + cofs + n * 16) = xo;
;         }
;         if (n == 1) __builtin_amdgcn_sched_barrier(0);
;       }
.LBB0_454:
	s_ashr_i32 s0, s47, 4
	v_or_b32_e32 v106, s14, v154
	s_mul_hi_i32 s1, s0, 0x6000
	s_mulk_i32 s0, 0x6000
	s_add_u32 s0, s28, s0
	v_ashrrev_i32_e32 v107, 31, v106
	s_addc_u32 s1, s37, s1
	v_lshlrev_b64 v[106:107], 2, v[106:107]
	v_lshl_add_u64 v[108:109], s[0:1], 0, v[106:107]
	s_mov_b64 s[0:1], 0x7102000
	v_lshl_add_u64 v[140:141], v[108:109], 0, s[0:1]
	s_load_dwordx2 s[0:1], s[4:5], 0x90
	v_lshl_add_u64 v[136:137], v[134:135], 0, s[12:13]
	v_lshl_add_u64 v[144:145], s[10:11], 0, v[106:107]
	v_lshlrev_b64 v[136:137], 12, v[136:137]
	v_lshl_add_u64 v[146:147], v[144:145], 0, v[136:137]
	s_waitcnt lgkmcnt(0)
	v_lshl_add_u64 v[138:139], s[0:1], 0, v[106:107]
	s_mov_b32 s0, 0x7102000
	v_add_co_u32_e32 v106, vcc, s0, v108
	v_lshl_add_u64 v[142:143], v[138:139], 0, v[136:137]
	s_nop 0
	v_addc_co_u32_e32 v107, vcc, 0, v109, vcc
	v_lshl_add_u64 v[180:181], v[144:145], 0, v[136:137]
	v_or_b32_e32 v196, 0x10000, v136
	v_mov_b32_e32 v197, v137
	v_lshl_add_u64 v[182:183], v[144:145], 0, v[196:197]
	v_or_b32_e32 v196, 0x20000, v136
	v_mov_b32_e32 v197, v137
	v_lshl_add_u64 v[184:185], v[144:145], 0, v[196:197]
	v_or_b32_e32 v196, 0x30000, v136
	v_mov_b32_e32 v197, v137
	v_lshl_add_u64 v[186:187], v[144:145], 0, v[196:197]
	v_or_b32_e32 v196, 0x40000, v136
	v_mov_b32_e32 v197, v137
	v_lshl_add_u64 v[188:189], v[144:145], 0, v[196:197]
	v_or_b32_e32 v196, 0x50000, v136
	v_mov_b32_e32 v197, v137
	v_lshl_add_u64 v[190:191], v[144:145], 0, v[196:197]
	v_or_b32_e32 v196, 0x60000, v136
	v_mov_b32_e32 v197, v137
	v_lshl_add_u64 v[192:193], v[144:145], 0, v[196:197]
	v_or_b32_e32 v196, 0x70000, v136
	v_mov_b32_e32 v197, v137
	v_lshl_add_u64 v[194:195], v[144:145], 0, v[196:197]
	v_sub_co_u32_e32 v198, vcc, v138, v144
	s_nop 1
	v_subb_co_u32_e32 v199, vcc, v139, v145, vcc
	global_load_dwordx4 v[200:203], v[140:141], off
	global_load_dwordx4 v[204:207], v[140:141], off offset:64
	global_load_dwordx4 v[208:211], v[140:141], off offset:128
	global_load_dwordx4 v[212:215], v[140:141], off offset:192
	global_load_dwordx4 v[216:219], v[180:181], off
	global_load_dwordx4 v[220:223], v[182:183], off
	global_load_dwordx4 v[224:227], v[184:185], off
	global_load_dwordx4 v[228:231], v[186:187], off
	global_load_dwordx4 v[232:235], v[188:189], off
	global_load_dwordx4 v[236:239], v[190:191], off
	global_load_dwordx4 v[240:243], v[192:193], off
	global_load_dwordx4 v[244:247], v[194:195], off
	global_load_dwordx4 v[248:251], v[180:181], off offset:64
	global_load_dwordx4 v[150:153], v[182:183], off offset:64
	global_load_dwordx4 v[156:159], v[184:185], off offset:64
	global_load_dwordx4 v[172:175], v[186:187], off offset:64
	global_load_dwordx4 v[106:109], v[188:189], off offset:64
	global_load_dwordx4 v[136:139], v[190:191], off offset:64
	global_load_dwordx4 v[144:147], v[192:193], off offset:64
	global_load_dwordx4 v[140:143], v[194:195], off offset:64
	s_waitcnt vmcnt(15)
	v_pk_fma_f32 v[130:131], v[200:201], v[130:131], v[216:217]
	v_pk_fma_f32 v[132:133], v[202:203], v[132:133], v[218:219]
	v_lshl_add_u64 v[196:197], v[180:181], 0, v[198:199]
	global_store_dwordx4 v[196:197], v[130:133], off
	global_load_dwordx4 v[216:219], v[180:181], off offset:128
	s_waitcnt vmcnt(16)
	v_pk_fma_f32 v[126:127], v[200:201], v[126:127], v[220:221]
	v_pk_fma_f32 v[128:129], v[202:203], v[128:129], v[222:223]
	v_lshl_add_u64 v[196:197], v[182:183], 0, v[198:199]
	global_store_dwordx4 v[196:197], v[126:129], off
	global_load_dwordx4 v[220:223], v[182:183], off offset:128
	s_waitcnt vmcnt(17)
	v_pk_fma_f32 v[122:123], v[200:201], v[122:123], v[224:225]
	v_pk_fma_f32 v[124:125], v[202:203], v[124:125], v[226:227]
	v_lshl_add_u64 v[196:197], v[184:185], 0, v[198:199]
	global_store_dwordx4 v[196:197], v[122:125], off
	global_load_dwordx4 v[224:227], v[184:185], off offset:128
	s_waitcnt vmcnt(18)
	v_pk_fma_f32 v[114:115], v[200:201], v[114:115], v[228:229]
	v_pk_fma_f32 v[116:117], v[202:203], v[116:117], v[230:231]
	v_lshl_add_u64 v[196:197], v[186:187], 0, v[198:199]
	global_store_dwordx4 v[196:197], v[114:117], off
	global_load_dwordx4 v[228:231], v[186:187], off offset:128
	s_waitcnt vmcnt(19)
	v_pk_fma_f32 v[118:119], v[200:201], v[118:119], v[232:233]
	v_pk_fma_f32 v[120:121], v[202:203], v[120:121], v[234:235]
	v_lshl_add_u64 v[196:197], v[188:189], 0, v[198:199]
	global_store_dwordx4 v[196:197], v[118:121], off
	global_load_dwordx4 v[232:235], v[188:189], off offset:128
	s_waitcnt vmcnt(20)
	v_pk_fma_f32 v[110:111], v[200:201], v[110:111], v[236:237]
	v_pk_fma_f32 v[112:113], v[202:203], v[112:113], v[238:239]
	v_lshl_add_u64 v[196:197], v[190:191], 0, v[198:199]
	global_store_dwordx4 v[196:197], v[110:113], off
	global_load_dwordx4 v[236:239], v[190:191], off offset:128
	s_waitcnt vmcnt(21)
	v_pk_fma_f32 v[102:103], v[200:201], v[102:103], v[240:241]
	v_pk_fma_f32 v[104:105], v[202:203], v[104:105], v[242:243]
	v_lshl_add_u64 v[196:197], v[192:193], 0, v[198:199]
	global_store_dwordx4 v[196:197], v[102:105], off
	global_load_dwordx4 v[240:243], v[192:193], off offset:128
	s_waitcnt vmcnt(22)
	v_pk_fma_f32 v[98:99], v[200:201], v[98:99], v[244:245]
	v_pk_fma_f32 v[100:101], v[202:203], v[100:101], v[246:247]
	v_lshl_add_u64 v[196:197], v[194:195], 0, v[198:199]
	global_store_dwordx4 v[196:197], v[98:101], off
	global_load_dwordx4 v[244:247], v[194:195], off offset:128
	s_waitcnt vmcnt(23)
	v_pk_fma_f32 v[94:95], v[204:205], v[94:95], v[248:249]
	v_pk_fma_f32 v[96:97], v[206:207], v[96:97], v[250:251]
	v_lshl_add_u64 v[196:197], v[180:181], 0, v[198:199]
	global_store_dwordx4 v[196:197], v[94:97], off offset:64
	global_load_dwordx4 v[248:251], v[180:181], off offset:192
	s_waitcnt vmcnt(24)
; __global__ void __launch_bounds__(NTHREADS, 2) fwd_megakernel(Params p_arg) {
;     ...
;       const float* gt = modl + (size_t)(brow >> 12) * 6144 + 2048;
; #pragma unroll
;       for (int n = 0; n < 4; ++n) {
;         const float4 g4 = *(const float4*)(gt + cofs + n * 16);
; #pragma unroll
;         for (int m = 0; m < 8; ++m) {
;           const size_t row = (size_t)brow + wr * 128 + m * 16 + fr;
;           float4 xo = *(const float4*)(xin + row * 1024 + cofs + n * 16);
;           xo.x += g4.x * acc[m][n][0]; xo.y += g4.y * acc[m][n][1]; xo.z += g4.z * acc[m][n][2]; xo.w += g4.w * acc[m][n][3];
;           *(float4*)(pk->out + row * 1024 + cofs + n * 16) = xo;
;         }
;         if (n == 1) __builtin_amdgcn_sched_barrier(0);
;       }
	v_pk_fma_f32 v[90:91], v[204:205], v[90:91], v[150:151]
	v_pk_fma_f32 v[92:93], v[206:207], v[92:93], v[152:153]
	v_lshl_add_u64 v[196:197], v[182:183], 0, v[198:199]
	global_store_dwordx4 v[196:197], v[90:93], off offset:64
	global_load_dwordx4 v[150:153], v[182:183], off offset:192
	s_waitcnt vmcnt(25)
	v_pk_fma_f32 v[86:87], v[204:205], v[86:87], v[156:157]
	v_pk_fma_f32 v[88:89], v[206:207], v[88:89], v[158:159]
	v_lshl_add_u64 v[196:197], v[184:185], 0, v[198:199]
	global_store_dwordx4 v[196:197], v[86:89], off offset:64
	global_load_dwordx4 v[156:159], v[184:185], off offset:192
	s_waitcnt vmcnt(26)
	v_pk_fma_f32 v[78:79], v[204:205], v[78:79], v[172:173]
	v_pk_fma_f32 v[80:81], v[206:207], v[80:81], v[174:175]
	v_lshl_add_u64 v[196:197], v[186:187], 0, v[198:199]
	global_store_dwordx4 v[196:197], v[78:81], off offset:64
	global_load_dwordx4 v[172:175], v[186:187], off offset:192
	s_waitcnt vmcnt(27)
	v_pk_fma_f32 v[82:83], v[204:205], v[82:83], v[106:107]
	v_pk_fma_f32 v[84:85], v[206:207], v[84:85], v[108:109]
	v_lshl_add_u64 v[196:197], v[188:189], 0, v[198:199]
	global_store_dwordx4 v[196:197], v[82:85], off offset:64
	global_load_dwordx4 v[106:109], v[188:189], off offset:192
	s_waitcnt vmcnt(28)
	v_pk_fma_f32 v[74:75], v[204:205], v[74:75], v[136:137]
	v_pk_fma_f32 v[76:77], v[206:207], v[76:77], v[138:139]
	v_lshl_add_u64 v[196:197], v[190:191], 0, v[198:199]
	global_store_dwordx4 v[196:197], v[74:77], off offset:64
	global_load_dwordx4 v[136:139], v[190:191], off offset:192
	s_waitcnt vmcnt(29)
	v_pk_fma_f32 v[70:71], v[204:205], v[70:71], v[144:145]
	v_pk_fma_f32 v[72:73], v[206:207], v[72:73], v[146:147]
	v_lshl_add_u64 v[196:197], v[192:193], 0, v[198:199]
	global_store_dwordx4 v[196:197], v[70:73], off offset:64
	global_load_dwordx4 v[144:147], v[192:193], off offset:192
	s_waitcnt vmcnt(30)
	v_pk_fma_f32 v[66:67], v[204:205], v[66:67], v[140:141]
	v_pk_fma_f32 v[68:69], v[206:207], v[68:69], v[142:143]
	v_lshl_add_u64 v[196:197], v[194:195], 0, v[198:199]
	global_store_dwordx4 v[196:197], v[66:69], off offset:64
	global_load_dwordx4 v[140:143], v[194:195], off offset:192
	s_waitcnt vmcnt(30)
	v_pk_fma_f32 v[62:63], v[208:209], v[62:63], v[216:217]
	v_pk_fma_f32 v[64:65], v[210:211], v[64:65], v[218:219]
	v_lshl_add_u64 v[196:197], v[180:181], 0, v[198:199]
	global_store_dwordx4 v[196:197], v[62:65], off offset:128
	s_waitcnt vmcnt(29)
	v_pk_fma_f32 v[58:59], v[208:209], v[58:59], v[220:221]
	v_pk_fma_f32 v[60:61], v[210:211], v[60:61], v[222:223]
	v_lshl_add_u64 v[196:197], v[182:183], 0, v[198:199]
	global_store_dwordx4 v[196:197], v[58:61], off offset:128
	s_waitcnt vmcnt(28)
	v_pk_fma_f32 v[50:51], v[208:209], v[50:51], v[224:225]
	v_pk_fma_f32 v[52:53], v[210:211], v[52:53], v[226:227]
	v_lshl_add_u64 v[196:197], v[184:185], 0, v[198:199]
	global_store_dwordx4 v[196:197], v[50:53], off offset:128
	s_waitcnt vmcnt(27)
	v_pk_fma_f32 v[42:43], v[208:209], v[42:43], v[228:229]
	v_pk_fma_f32 v[44:45], v[210:211], v[44:45], v[230:231]
	v_lshl_add_u64 v[196:197], v[186:187], 0, v[198:199]
	global_store_dwordx4 v[196:197], v[42:45], off offset:128
	s_waitcnt vmcnt(26)
	v_pk_fma_f32 v[54:55], v[208:209], v[54:55], v[232:233]
	v_pk_fma_f32 v[56:57], v[210:211], v[56:57], v[234:235]
	v_lshl_add_u64 v[196:197], v[188:189], 0, v[198:199]
	global_store_dwordx4 v[196:197], v[54:57], off offset:128
	s_waitcnt vmcnt(25)
	v_pk_fma_f32 v[46:47], v[208:209], v[46:47], v[236:237]
	v_pk_fma_f32 v[48:49], v[210:211], v[48:49], v[238:239]
	v_lshl_add_u64 v[196:197], v[190:191], 0, v[198:199]
	global_store_dwordx4 v[196:197], v[46:49], off offset:128
	s_waitcnt vmcnt(24)
	v_pk_fma_f32 v[38:39], v[208:209], v[38:39], v[240:241]
	v_pk_fma_f32 v[40:41], v[210:211], v[40:41], v[242:243]
	v_lshl_add_u64 v[196:197], v[192:193], 0, v[198:199]
	global_store_dwordx4 v[196:197], v[38:41], off offset:128
	s_waitcnt vmcnt(23)
	v_pk_fma_f32 v[34:35], v[208:209], v[34:35], v[244:245]
	v_pk_fma_f32 v[36:37], v[210:211], v[36:37], v[246:247]
	v_lshl_add_u64 v[196:197], v[194:195], 0, v[198:199]
	global_store_dwordx4 v[196:197], v[34:37], off offset:128
	s_waitcnt vmcnt(22)
	v_pk_fma_f32 v[30:31], v[212:213], v[30:31], v[248:249]
	v_pk_fma_f32 v[32:33], v[214:215], v[32:33], v[250:251]
	v_lshl_add_u64 v[196:197], v[180:181], 0, v[198:199]
	global_store_dwordx4 v[196:197], v[30:33], off offset:192
	s_waitcnt vmcnt(21)
	v_pk_fma_f32 v[26:27], v[212:213], v[26:27], v[150:151]
	v_pk_fma_f32 v[28:29], v[214:215], v[28:29], v[152:153]
	v_lshl_add_u64 v[196:197], v[182:183], 0, v[198:199]
	global_store_dwordx4 v[196:197], v[26:29], off offset:192
	s_waitcnt vmcnt(20)
	v_pk_fma_f32 v[18:19], v[212:213], v[18:19], v[156:157]
	v_pk_fma_f32 v[20:21], v[214:215], v[20:21], v[158:159]
	v_lshl_add_u64 v[196:197], v[184:185], 0, v[198:199]
	global_store_dwordx4 v[196:197], v[18:21], off offset:192
	s_waitcnt vmcnt(19)
	v_pk_fma_f32 v[10:11], v[212:213], v[10:11], v[172:173]
	v_pk_fma_f32 v[12:13], v[214:215], v[12:13], v[174:175]
	v_lshl_add_u64 v[196:197], v[186:187], 0, v[198:199]
	global_store_dwordx4 v[196:197], v[10:13], off offset:192
	s_waitcnt vmcnt(18)
	v_pk_fma_f32 v[22:23], v[212:213], v[22:23], v[106:107]
	v_pk_fma_f32 v[24:25], v[214:215], v[24:25], v[108:109]
	v_lshl_add_u64 v[196:197], v[188:189], 0, v[198:199]
	global_store_dwordx4 v[196:197], v[22:25], off offset:192
	s_waitcnt vmcnt(17)
	v_pk_fma_f32 v[14:15], v[212:213], v[14:15], v[136:137]
	v_pk_fma_f32 v[16:17], v[214:215], v[16:17], v[138:139]
	v_lshl_add_u64 v[196:197], v[190:191], 0, v[198:199]
	global_store_dwordx4 v[196:197], v[14:17], off offset:192
	s_waitcnt vmcnt(16)
	v_pk_fma_f32 v[6:7], v[212:213], v[6:7], v[144:145]
	v_pk_fma_f32 v[8:9], v[214:215], v[8:9], v[146:147]
	v_lshl_add_u64 v[196:197], v[192:193], 0, v[198:199]
	global_store_dwordx4 v[196:197], v[6:9], off offset:192
	s_waitcnt vmcnt(15)
	v_pk_fma_f32 v[2:3], v[212:213], v[2:3], v[140:141]
	v_pk_fma_f32 v[4:5], v[214:215], v[4:5], v[142:143]
	v_lshl_add_u64 v[196:197], v[194:195], 0, v[198:199]
	global_store_dwordx4 v[196:197], v[2:5], off offset:192
	s_mov_b64 s[0:1], 0xc0
	s_mov_b64 s[52:53], 0xc0
	s_add_i32 s44, s44, 1
	s_mov_b64 s[98:99], s[54:55]
	s_mov_b64 s[0:1], 0

; __global__ void __launch_bounds__(NTHREADS, 2) fwd_megakernel(Params p_arg) {
;     ...
;       const float* gt = modl + (size_t)(brow >> 12) * 6144 + 5120;
; #pragma unroll
;       for (int n = 0; n < 4; ++n) {
;         const float4 g4 = *(const float4*)(gt + cofs + n * 16);
; #pragma unroll
;         for (int m = 0; m < 8; ++m) {
;           const size_t row = (size_t)brow + wr * 128 + m * 16 + fr;
;           float4 xo = *(const float4*)(pk->out + row * 1024 + cofs + n * 16);
;           xo.x += g4.x * acc[m][n][0]; xo.y += g4.y * acc[m][n][1]; xo.z += g4.z * acc[m][n][2]; xo.w += g4.w * acc[m][n][3];
;           *(float4*)(pk->out + row * 1024 + cofs + n * 16) = xo;
;         }
;         if (n == 1) __builtin_amdgcn_sched_barrier(0);
;       }
.LBB0_670:
	s_ashr_i32 s0, s20, 4
	v_or_b32_e32 v132, s21, v144
	s_mul_hi_i32 s1, s0, 0x6000
	s_mulk_i32 s0, 0x6000
	s_add_u32 s0, s12, s0
	v_ashrrev_i32_e32 v133, 31, v132
	s_addc_u32 s1, s13, s1
	v_lshlrev_b64 v[132:133], 2, v[132:133]
	v_lshl_add_u64 v[146:147], s[0:1], 0, v[132:133]
	s_mov_b64 s[0:1], 0x7105000
	v_lshl_add_u64 v[134:135], v[146:147], 0, s[0:1]
	s_load_dwordx2 s[0:1], s[4:5], 0x90
	v_lshl_add_u64 v[136:137], v[130:131], 0, s[6:7]
	s_waitcnt lgkmcnt(0)
	v_lshl_add_u64 v[138:139], s[0:1], 0, v[132:133]
	s_mov_b32 s0, 0x7105000
	v_add_co_u32_e32 v146, vcc, s0, v146
	v_lshlrev_b64 v[132:133], 12, v[136:137]
	s_nop 0
	v_addc_co_u32_e32 v147, vcc, 0, v147, vcc
	v_lshl_add_u64 v[136:137], v[138:139], 0, v[132:133]
	v_lshl_add_u64 v[180:181], v[138:139], 0, v[132:133]
	v_or_b32_e32 v196, 0x10000, v132
	v_mov_b32_e32 v197, v133
	v_lshl_add_u64 v[182:183], v[138:139], 0, v[196:197]
	v_or_b32_e32 v196, 0x20000, v132
	v_mov_b32_e32 v197, v133
	v_lshl_add_u64 v[184:185], v[138:139], 0, v[196:197]
	v_or_b32_e32 v196, 0x30000, v132
	v_mov_b32_e32 v197, v133
	v_lshl_add_u64 v[186:187], v[138:139], 0, v[196:197]
	v_or_b32_e32 v196, 0x40000, v132
	v_mov_b32_e32 v197, v133
	v_lshl_add_u64 v[188:189], v[138:139], 0, v[196:197]
	v_or_b32_e32 v196, 0x50000, v132
	v_mov_b32_e32 v197, v133
	v_lshl_add_u64 v[190:191], v[138:139], 0, v[196:197]
	v_or_b32_e32 v196, 0x60000, v132
	v_mov_b32_e32 v197, v133
	v_lshl_add_u64 v[192:193], v[138:139], 0, v[196:197]
	v_or_b32_e32 v196, 0x70000, v132
	v_mov_b32_e32 v197, v133
	v_lshl_add_u64 v[194:195], v[138:139], 0, v[196:197]
	global_load_dwordx4 v[200:203], v[134:135], off
	global_load_dwordx4 v[204:207], v[134:135], off offset:64
	global_load_dwordx4 v[208:211], v[134:135], off offset:128
	global_load_dwordx4 v[212:215], v[134:135], off offset:192
	global_load_dwordx4 v[216:219], v[180:181], off
	global_load_dwordx4 v[220:223], v[182:183], off
	global_load_dwordx4 v[224:227], v[184:185], off
	global_load_dwordx4 v[228:231], v[186:187], off
	global_load_dwordx4 v[232:235], v[188:189], off
	global_load_dwordx4 v[236:239], v[190:191], off
	global_load_dwordx4 v[240:243], v[192:193], off
	global_load_dwordx4 v[244:247], v[194:195], off
	global_load_dwordx4 v[248:251], v[180:181], off offset:64
	global_load_dwordx4 v[150:153], v[182:183], off offset:64
	global_load_dwordx4 v[154:157], v[184:185], off offset:64
	global_load_dwordx4 v[158:161], v[186:187], off offset:64
	global_load_dwordx4 v[172:175], v[188:189], off offset:64
	global_load_dwordx4 v[132:135], v[190:191], off offset:64
	global_load_dwordx4 v[136:139], v[192:193], off offset:64
	global_load_dwordx4 v[196:199], v[194:195], off offset:64
	s_waitcnt vmcnt(15)
	v_pk_fma_f32 v[126:127], v[200:201], v[126:127], v[216:217]
	v_pk_fma_f32 v[128:129], v[202:203], v[128:129], v[218:219]
	global_store_dwordx4 v[180:181], v[126:129], off
	global_load_dwordx4 v[216:219], v[180:181], off offset:128
	s_waitcnt vmcnt(16)
	v_pk_fma_f32 v[122:123], v[200:201], v[122:123], v[220:221]
	v_pk_fma_f32 v[124:125], v[202:203], v[124:125], v[222:223]
	global_store_dwordx4 v[182:183], v[122:125], off
	global_load_dwordx4 v[220:223], v[182:183], off offset:128
	s_waitcnt vmcnt(17)
	v_pk_fma_f32 v[118:119], v[200:201], v[118:119], v[224:225]
	v_pk_fma_f32 v[120:121], v[202:203], v[120:121], v[226:227]
	global_store_dwordx4 v[184:185], v[118:121], off
	global_load_dwordx4 v[224:227], v[184:185], off offset:128
	s_waitcnt vmcnt(18)
	v_pk_fma_f32 v[110:111], v[200:201], v[110:111], v[228:229]
	v_pk_fma_f32 v[112:113], v[202:203], v[112:113], v[230:231]
	global_store_dwordx4 v[186:187], v[110:113], off
	global_load_dwordx4 v[228:231], v[186:187], off offset:128
	s_waitcnt vmcnt(19)
	v_pk_fma_f32 v[114:115], v[200:201], v[114:115], v[232:233]
	v_pk_fma_f32 v[116:117], v[202:203], v[116:117], v[234:235]
	global_store_dwordx4 v[188:189], v[114:117], off
	global_load_dwordx4 v[232:235], v[188:189], off offset:128
	s_waitcnt vmcnt(20)
	v_pk_fma_f32 v[106:107], v[200:201], v[106:107], v[236:237]
	v_pk_fma_f32 v[108:109], v[202:203], v[108:109], v[238:239]
	global_store_dwordx4 v[190:191], v[106:109], off
	global_load_dwordx4 v[236:239], v[190:191], off offset:128
	s_waitcnt vmcnt(21)
	v_pk_fma_f32 v[102:103], v[200:201], v[102:103], v[240:241]
	v_pk_fma_f32 v[104:105], v[202:203], v[104:105], v[242:243]
	global_store_dwordx4 v[192:193], v[102:105], off
	global_load_dwordx4 v[240:243], v[192:193], off offset:128
	s_waitcnt vmcnt(22)
	v_pk_fma_f32 v[98:99], v[200:201], v[98:99], v[244:245]
	v_pk_fma_f32 v[100:101], v[202:203], v[100:101], v[246:247]
	global_store_dwordx4 v[194:195], v[98:101], off
	global_load_dwordx4 v[244:247], v[194:195], off offset:128
	s_waitcnt vmcnt(23)
	v_pk_fma_f32 v[86:87], v[204:205], v[86:87], v[248:249]
	v_pk_fma_f32 v[88:89], v[206:207], v[88:89], v[250:251]
	global_store_dwordx4 v[180:181], v[86:89], off offset:64
	global_load_dwordx4 v[248:251], v[180:181], off offset:192
	s_waitcnt vmcnt(24)
; __global__ void __launch_bounds__(NTHREADS, 2) fwd_megakernel(Params p_arg) {
;     ...
;       const int cofs = bcol + wc * 64 + fq * 4;
;       const float* gt = modl + (size_t)(brow >> 12) * 6144 + 5120;
; #pragma unroll
;       for (int n = 0; n < 4; ++n) {
;         const float4 g4 = *(const float4*)(gt + cofs + n * 16);
; #pragma unroll
;         for (int m = 0; m < 8; ++m) {
;           const size_t row = (size_t)brow + wr * 128 + m * 16 + fr;
;           float4 xo = *(const float4*)(pk->out + row * 1024 + cofs + n * 16);
;           xo.x += g4.x * acc[m][n][0]; xo.y += g4.y * acc[m][n][1]; xo.z += g4.z * acc[m][n][2]; xo.w += g4.w * acc[m][n][3];
;           *(float4*)(pk->out + row * 1024 + cofs + n * 16) = xo;
;         }
;         if (n == 1) __builtin_amdgcn_sched_barrier(0);
;       }
	v_pk_fma_f32 v[90:91], v[204:205], v[90:91], v[150:151]
	v_pk_fma_f32 v[92:93], v[206:207], v[92:93], v[152:153]
	global_store_dwordx4 v[182:183], v[90:93], off offset:64
	global_load_dwordx4 v[150:153], v[182:183], off offset:192
	s_waitcnt vmcnt(25)
	v_pk_fma_f32 v[94:95], v[204:205], v[94:95], v[154:155]
	v_pk_fma_f32 v[96:97], v[206:207], v[96:97], v[156:157]
	global_store_dwordx4 v[184:185], v[94:97], off offset:64
	global_load_dwordx4 v[154:157], v[184:185], off offset:192
	s_waitcnt vmcnt(26)
	v_pk_fma_f32 v[82:83], v[204:205], v[82:83], v[158:159]
	v_pk_fma_f32 v[84:85], v[206:207], v[84:85], v[160:161]
	global_store_dwordx4 v[186:187], v[82:85], off offset:64
	global_load_dwordx4 v[158:161], v[186:187], off offset:192
	s_waitcnt vmcnt(27)
	v_pk_fma_f32 v[78:79], v[204:205], v[78:79], v[172:173]
	v_pk_fma_f32 v[80:81], v[206:207], v[80:81], v[174:175]
	global_store_dwordx4 v[188:189], v[78:81], off offset:64
	global_load_dwordx4 v[172:175], v[188:189], off offset:192
	s_waitcnt vmcnt(28)
	v_pk_fma_f32 v[74:75], v[204:205], v[74:75], v[132:133]
	v_pk_fma_f32 v[76:77], v[206:207], v[76:77], v[134:135]
	global_store_dwordx4 v[190:191], v[74:77], off offset:64
	global_load_dwordx4 v[132:135], v[190:191], off offset:192
	s_waitcnt vmcnt(29)
	v_pk_fma_f32 v[70:71], v[204:205], v[70:71], v[136:137]
	v_pk_fma_f32 v[72:73], v[206:207], v[72:73], v[138:139]
	global_store_dwordx4 v[192:193], v[70:73], off offset:64
	global_load_dwordx4 v[136:139], v[192:193], off offset:192
	s_waitcnt vmcnt(30)
	v_pk_fma_f32 v[66:67], v[204:205], v[66:67], v[196:197]
	v_pk_fma_f32 v[68:69], v[206:207], v[68:69], v[198:199]
	global_store_dwordx4 v[194:195], v[66:69], off offset:64
	global_load_dwordx4 v[196:199], v[194:195], off offset:192
	s_waitcnt vmcnt(30)
	v_pk_fma_f32 v[62:63], v[208:209], v[62:63], v[216:217]
	v_pk_fma_f32 v[64:65], v[210:211], v[64:65], v[218:219]
	global_store_dwordx4 v[180:181], v[62:65], off offset:128
	s_waitcnt vmcnt(29)
	v_pk_fma_f32 v[58:59], v[208:209], v[58:59], v[220:221]
	v_pk_fma_f32 v[60:61], v[210:211], v[60:61], v[222:223]
	global_store_dwordx4 v[182:183], v[58:61], off offset:128
	s_waitcnt vmcnt(28)
	v_pk_fma_f32 v[54:55], v[208:209], v[54:55], v[224:225]
	v_pk_fma_f32 v[56:57], v[210:211], v[56:57], v[226:227]
	global_store_dwordx4 v[184:185], v[54:57], off offset:128
	s_waitcnt vmcnt(27)
	v_pk_fma_f32 v[46:47], v[208:209], v[46:47], v[228:229]
	v_pk_fma_f32 v[48:49], v[210:211], v[48:49], v[230:231]
	global_store_dwordx4 v[186:187], v[46:49], off offset:128
	s_waitcnt vmcnt(26)
	v_pk_fma_f32 v[50:51], v[208:209], v[50:51], v[232:233]
	v_pk_fma_f32 v[52:53], v[210:211], v[52:53], v[234:235]
	global_store_dwordx4 v[188:189], v[50:53], off offset:128
	s_waitcnt vmcnt(25)
	v_pk_fma_f32 v[42:43], v[208:209], v[42:43], v[236:237]
	v_pk_fma_f32 v[44:45], v[210:211], v[44:45], v[238:239]
	global_store_dwordx4 v[190:191], v[42:45], off offset:128
	s_waitcnt vmcnt(24)
	v_pk_fma_f32 v[38:39], v[208:209], v[38:39], v[240:241]
	v_pk_fma_f32 v[40:41], v[210:211], v[40:41], v[242:243]
	global_store_dwordx4 v[192:193], v[38:41], off offset:128
	s_waitcnt vmcnt(23)
	v_pk_fma_f32 v[34:35], v[208:209], v[34:35], v[244:245]
	v_pk_fma_f32 v[36:37], v[210:211], v[36:37], v[246:247]
	global_store_dwordx4 v[194:195], v[34:37], off offset:128
	s_waitcnt vmcnt(22)
	v_pk_fma_f32 v[22:23], v[212:213], v[22:23], v[248:249]
	v_pk_fma_f32 v[24:25], v[214:215], v[24:25], v[250:251]
	global_store_dwordx4 v[180:181], v[22:25], off offset:192
	s_waitcnt vmcnt(21)
	v_pk_fma_f32 v[26:27], v[212:213], v[26:27], v[150:151]
	v_pk_fma_f32 v[28:29], v[214:215], v[28:29], v[152:153]
	global_store_dwordx4 v[182:183], v[26:29], off offset:192
	s_waitcnt vmcnt(20)
	v_pk_fma_f32 v[30:31], v[212:213], v[30:31], v[154:155]
	v_pk_fma_f32 v[32:33], v[214:215], v[32:33], v[156:157]
	global_store_dwordx4 v[184:185], v[30:33], off offset:192
	s_waitcnt vmcnt(19)
	v_pk_fma_f32 v[18:19], v[212:213], v[18:19], v[158:159]
	v_pk_fma_f32 v[20:21], v[214:215], v[20:21], v[160:161]
	global_store_dwordx4 v[186:187], v[18:21], off offset:192
	s_waitcnt vmcnt(18)
	v_pk_fma_f32 v[14:15], v[212:213], v[14:15], v[172:173]
	v_pk_fma_f32 v[16:17], v[214:215], v[16:17], v[174:175]
	global_store_dwordx4 v[188:189], v[14:17], off offset:192
	s_waitcnt vmcnt(17)
	v_pk_fma_f32 v[10:11], v[212:213], v[10:11], v[132:133]
	v_pk_fma_f32 v[12:13], v[214:215], v[12:13], v[134:135]
	global_store_dwordx4 v[190:191], v[10:13], off offset:192
	s_waitcnt vmcnt(16)
	v_pk_fma_f32 v[6:7], v[212:213], v[6:7], v[136:137]
	v_pk_fma_f32 v[8:9], v[214:215], v[8:9], v[138:139]
	global_store_dwordx4 v[192:193], v[6:9], off offset:192
	s_waitcnt vmcnt(15)
	v_pk_fma_f32 v[2:3], v[212:213], v[2:3], v[196:197]
	v_pk_fma_f32 v[4:5], v[214:215], v[4:5], v[198:199]
	global_store_dwordx4 v[194:195], v[2:5], off offset:192
	s_add_i32 s19, s19, 1
	s_mov_b64 s[0:1], 0
